# 13-round block search with the GEMM main loops pinned to the byte phases of the best version
# baseline (speedup 1.0000x reference)
; template <class Epi, class Sched, bool ALIGN_EPI = false, bool SP2 = false>
; __device__ __forceinline__ void gemm_phase(LAS unsigned char* lds, const Gemm g, const Sched& S, const Epi& E, const int tid) {
;     ...
;     for (;;) {
;         const bool has_next = S.next(ui + 1, nxt);
;         const char* nA = has_next ? (const char*)g.A + (size_t)nxt.pm * tstep : cA; const char* nB = has_next ? (const char*)g.Bt + (size_t)nxt.pn * tstep : cB;
;         for (int t = 0; t < nt; t += 2) {
;             const bool last = (t == nt - 2);
;             const char* a1 = cA + (size_t)(t + 1) * kstep;
;             const char* a2 = last ? nA : cA + (size_t)(t + 2) * kstep; const char* b2 = last ? nB : cB + (size_t)(t + 2) * kstep;
;     ...
; #pragma unroll
;         for (int a = 0; a < 2; ++a)
; #pragma unroll
;             for (int b = 0; b < 2; ++b)
; #pragma unroll
;                 for (int m = 0; m < 4; ++m)
; #pragma unroll
;                     for (int n = 0; n < 2; ++n) acc[a][b][m][n] = (f32x4){0.f, 0.f, 0.f, 0.f};
;         cur = nxt; cA = nA; cB = nB; ++ui;
.LBB0_366:
	s_ashr_i32 s31, s30, 31
	s_lshl_b64 s[0:1], s[30:31], 20
	s_add_u32 s34, s46, s0
	s_addc_u32 s35, s47, s1
	s_and_b64 s[0:1], s[2:3], exec
	s_cselect_b32 s7, s35, s39
	s_cselect_b32 s9, s34, s38
	s_ashr_i32 s29, s28, 31
	s_lshl_b64 s[0:1], s[28:29], 20
	s_add_u32 s36, s48, s0
	s_addc_u32 s37, s49, s1
	s_and_b64 s[0:1], s[2:3], exec
	s_cselect_b32 s29, s37, s5
	s_cselect_b32 s31, s36, s4
	s_add_u32 s0, s38, 0x80080
	s_addc_u32 s1, s39, 0
	s_add_u32 s61, s4, 0x100
	v_mov_b32_e32 v0, 0
	s_addc_u32 s62, s5, 0
	s_mov_b32 s63, -2
	v_mov_b32_e32 v1, v0
	v_mov_b32_e32 v2, v0
	v_mov_b32_e32 v3, v0
	v_mov_b32_e32 v4, v0
	v_mov_b32_e32 v5, v0
	v_mov_b32_e32 v6, v0
	v_mov_b32_e32 v7, v0
	v_mov_b32_e32 v16, v0
	v_mov_b32_e32 v17, v0
	v_mov_b32_e32 v18, v0
	v_mov_b32_e32 v19, v0
	v_mov_b32_e32 v20, v0
	v_mov_b32_e32 v21, v0
	v_mov_b32_e32 v22, v0
	v_mov_b32_e32 v23, v0
	v_mov_b32_e32 v32, v0
	v_mov_b32_e32 v33, v0
	v_mov_b32_e32 v34, v0
	v_mov_b32_e32 v35, v0
	v_mov_b32_e32 v36, v0
	v_mov_b32_e32 v37, v0
	v_mov_b32_e32 v38, v0
	v_mov_b32_e32 v39, v0
	v_mov_b32_e32 v48, v0
	v_mov_b32_e32 v49, v0
	v_mov_b32_e32 v50, v0
	v_mov_b32_e32 v51, v0
	v_mov_b32_e32 v52, v0
	v_mov_b32_e32 v53, v0
	v_mov_b32_e32 v54, v0
	v_mov_b32_e32 v55, v0
	v_mov_b32_e32 v8, v0
	v_mov_b32_e32 v9, v0
	v_mov_b32_e32 v10, v0
	v_mov_b32_e32 v11, v0
	v_mov_b32_e32 v12, v0
	v_mov_b32_e32 v13, v0
	v_mov_b32_e32 v14, v0
	v_mov_b32_e32 v15, v0
	v_mov_b32_e32 v24, v0
	v_mov_b32_e32 v25, v0
	v_mov_b32_e32 v26, v0
	v_mov_b32_e32 v27, v0
	v_mov_b32_e32 v28, v0
	v_mov_b32_e32 v29, v0
	v_mov_b32_e32 v30, v0
	v_mov_b32_e32 v31, v0
	v_mov_b32_e32 v40, v0
	v_mov_b32_e32 v41, v0
	v_mov_b32_e32 v42, v0
	v_mov_b32_e32 v43, v0
	v_mov_b32_e32 v44, v0
	v_mov_b32_e32 v45, v0
	v_mov_b32_e32 v46, v0
	v_mov_b32_e32 v47, v0
	v_mov_b32_e32 v56, v0
	v_mov_b32_e32 v57, v0
	v_mov_b32_e32 v58, v0
	v_mov_b32_e32 v59, v0
	v_mov_b32_e32 v60, v0
	v_mov_b32_e32 v61, v0
	v_mov_b32_e32 v62, v0
	v_mov_b32_e32 v63, v0
	v_mov_b32_e32 v64, v0
	v_mov_b32_e32 v65, v0
	v_mov_b32_e32 v66, v0
	v_mov_b32_e32 v67, v0
	v_mov_b32_e32 v68, v0
	v_mov_b32_e32 v69, v0
	v_mov_b32_e32 v70, v0
	v_mov_b32_e32 v71, v0
	v_mov_b32_e32 v80, v0
	v_mov_b32_e32 v81, v0
	v_mov_b32_e32 v82, v0
	v_mov_b32_e32 v83, v0
	v_mov_b32_e32 v84, v0
	v_mov_b32_e32 v85, v0
	v_mov_b32_e32 v86, v0
	v_mov_b32_e32 v87, v0
	v_mov_b32_e32 v96, v0
	v_mov_b32_e32 v97, v0
	v_mov_b32_e32 v98, v0
	v_mov_b32_e32 v99, v0
	v_mov_b32_e32 v100, v0
	v_mov_b32_e32 v101, v0
	v_mov_b32_e32 v102, v0
	v_mov_b32_e32 v103, v0
	v_mov_b32_e32 v112, v0
	v_mov_b32_e32 v113, v0
	v_mov_b32_e32 v114, v0
	v_mov_b32_e32 v115, v0
	v_mov_b32_e32 v116, v0
	v_mov_b32_e32 v117, v0
	v_mov_b32_e32 v118, v0
	v_mov_b32_e32 v119, v0
	v_mov_b32_e32 v72, v0
	v_mov_b32_e32 v73, v0
	v_mov_b32_e32 v74, v0
	v_mov_b32_e32 v75, v0
	v_mov_b32_e32 v76, v0
	v_mov_b32_e32 v77, v0
	v_mov_b32_e32 v78, v0
	v_mov_b32_e32 v79, v0
	v_mov_b32_e32 v88, v0
	v_mov_b32_e32 v89, v0
	v_mov_b32_e32 v90, v0
	v_mov_b32_e32 v91, v0
	v_mov_b32_e32 v92, v0
	v_mov_b32_e32 v93, v0
	v_mov_b32_e32 v94, v0
	v_mov_b32_e32 v95, v0
	v_mov_b32_e32 v104, v0
	v_mov_b32_e32 v105, v0
	v_mov_b32_e32 v106, v0
	v_mov_b32_e32 v107, v0
	v_mov_b32_e32 v108, v0
	v_mov_b32_e32 v109, v0
	v_mov_b32_e32 v110, v0
	v_mov_b32_e32 v111, v0
	v_mov_b32_e32 v120, v0
	v_mov_b32_e32 v121, v0
	v_mov_b32_e32 v122, v0
	v_mov_b32_e32 v123, v0
	v_mov_b32_e32 v124, v0
	v_mov_b32_e32 v125, v0
	v_mov_b32_e32 v126, v0
	v_mov_b32_e32 v127, v0
	.p2align 6
	s_nop 0
	s_nop 0
	s_nop 0
	s_nop 0

; template <class Epi, class Sched, bool ALIGN_EPI = false, bool SP2 = false>
; __device__ __forceinline__ void gemm_phase(LAS unsigned char* lds, const Gemm g, const Sched& S, const Epi& E, const int tid) {
;     ...
;     for (;;) {
;         const bool has_next = S.next(ui + 1, nxt);
;         const char* nA = has_next ? (const char*)g.A + (size_t)nxt.pm * tstep : cA; const char* nB = has_next ? (const char*)g.Bt + (size_t)nxt.pn * tstep : cB;
;         for (int t = 0; t < nt; t += 2) {
;             const bool last = (t == nt - 2);
;             const char* a1 = cA + (size_t)(t + 1) * kstep;
;             const char* a2 = last ? nA : cA + (size_t)(t + 2) * kstep; const char* b2 = last ? nB : cB + (size_t)(t + 2) * kstep;
;     ...
; #pragma unroll
;         for (int a = 0; a < 2; ++a)
; #pragma unroll
;             for (int b = 0; b < 2; ++b)
; #pragma unroll
;                 for (int m = 0; m < 4; ++m)
; #pragma unroll
;                     for (int n = 0; n < 2; ++n) acc[a][b][m][n] = (f32x4){0.f, 0.f, 0.f, 0.f};
;         cur = nxt; cA = nA; cB = nB; ++ui;
.LBB0_1314:
	s_ashr_i32 s17, s16, 31
	s_lshl_b64 s[18:19], s[16:17], 19
	s_add_u32 s18, s31, s18
	s_addc_u32 s19, s34, s19
	s_and_b64 s[20:21], s[2:3], exec
	s_cselect_b32 s17, s19, s23
	s_cselect_b32 s46, s18, s22
	s_ashr_i32 s15, s14, 31
	s_lshl_b64 s[20:21], s[14:15], 19
	s_add_u32 s20, s35, s20
	s_addc_u32 s21, s36, s21
	s_and_b64 s[26:27], s[2:3], exec
	s_cselect_b32 s15, s21, s25
	s_cselect_b32 s47, s20, s24
	s_add_u32 s22, s22, 0x40080
	s_addc_u32 s23, s23, 0
	s_add_u32 s48, s24, 0x100
	v_mov_b32_e32 v4, 0
	s_addc_u32 s49, s25, 0
	s_mov_b32 s50, -2
	v_mov_b32_e32 v5, v4
	v_mov_b32_e32 v6, v4
	v_mov_b32_e32 v7, v4
	v_mov_b32_e32 v0, v4
	v_mov_b32_e32 v1, v4
	v_mov_b32_e32 v2, v4
	v_mov_b32_e32 v3, v4
	v_mov_b32_e32 v20, v4
	v_mov_b32_e32 v21, v4
	v_mov_b32_e32 v22, v4
	v_mov_b32_e32 v23, v4
	v_mov_b32_e32 v16, v4
	v_mov_b32_e32 v17, v4
	v_mov_b32_e32 v18, v4
	v_mov_b32_e32 v19, v4
	v_mov_b32_e32 v36, v4
	v_mov_b32_e32 v37, v4
	v_mov_b32_e32 v38, v4
	v_mov_b32_e32 v39, v4
	v_mov_b32_e32 v32, v4
	v_mov_b32_e32 v33, v4
	v_mov_b32_e32 v34, v4
	v_mov_b32_e32 v35, v4
	v_mov_b32_e32 v52, v4
	v_mov_b32_e32 v53, v4
	v_mov_b32_e32 v54, v4
	v_mov_b32_e32 v55, v4
	v_mov_b32_e32 v48, v4
	v_mov_b32_e32 v49, v4
	s_waitcnt vmcnt(0)
	v_mov_b32_e32 v50, v4
	v_mov_b32_e32 v51, v4
	v_mov_b32_e32 v8, v4
	v_mov_b32_e32 v9, v4
	v_mov_b32_e32 v10, v4
	v_mov_b32_e32 v11, v4
	v_mov_b32_e32 v12, v4
	v_mov_b32_e32 v13, v4
	v_mov_b32_e32 v14, v4
	v_mov_b32_e32 v15, v4
	v_mov_b32_e32 v24, v4
	v_mov_b32_e32 v25, v4
	v_mov_b32_e32 v26, v4
	v_mov_b32_e32 v27, v4
	v_mov_b32_e32 v28, v4
	v_mov_b32_e32 v29, v4
	v_mov_b32_e32 v30, v4
	v_mov_b32_e32 v31, v4
	v_mov_b32_e32 v40, v4
	v_mov_b32_e32 v41, v4
	v_mov_b32_e32 v42, v4
	v_mov_b32_e32 v43, v4
	v_mov_b32_e32 v44, v4
	v_mov_b32_e32 v45, v4
	v_mov_b32_e32 v46, v4
	v_mov_b32_e32 v47, v4
	v_mov_b32_e32 v56, v4
	v_mov_b32_e32 v57, v4
	v_mov_b32_e32 v58, v4
	v_mov_b32_e32 v59, v4
	v_mov_b32_e32 v60, v4
	v_mov_b32_e32 v61, v4
	v_mov_b32_e32 v62, v4
	v_mov_b32_e32 v63, v4
	v_mov_b32_e32 v68, v4
	v_mov_b32_e32 v69, v4
	v_mov_b32_e32 v70, v4
	v_mov_b32_e32 v71, v4
	v_mov_b32_e32 v64, v4
	v_mov_b32_e32 v65, v4
	v_mov_b32_e32 v66, v4
	v_mov_b32_e32 v67, v4
	v_mov_b32_e32 v100, v4
	v_mov_b32_e32 v101, v4
	v_mov_b32_e32 v102, v4
	v_mov_b32_e32 v103, v4
	v_mov_b32_e32 v96, v4
	v_mov_b32_e32 v97, v4
	v_mov_b32_e32 v98, v4
	v_mov_b32_e32 v99, v4
	v_mov_b32_e32 v116, v4
	v_mov_b32_e32 v117, v4
	v_mov_b32_e32 v118, v4
	v_mov_b32_e32 v119, v4
	v_mov_b32_e32 v112, v4
	v_mov_b32_e32 v113, v4
	v_mov_b32_e32 v114, v4
	v_mov_b32_e32 v115, v4
	v_mov_b32_e32 v128, v4
	v_mov_b32_e32 v129, v4
	v_mov_b32_e32 v130, v4
	v_mov_b32_e32 v131, v4
	v_mov_b32_e32 v132, v4
	v_mov_b32_e32 v133, v4
	v_mov_b32_e32 v134, v4
	v_mov_b32_e32 v135, v4
	v_mov_b32_e32 v80, v4
	v_mov_b32_e32 v81, v4
	v_mov_b32_e32 v82, v4
	v_mov_b32_e32 v83, v4
	v_mov_b32_e32 v84, v4
	v_mov_b32_e32 v85, v4
	v_mov_b32_e32 v86, v4
	v_mov_b32_e32 v87, v4
	v_mov_b32_e32 v104, v4
	v_mov_b32_e32 v105, v4
	v_mov_b32_e32 v106, v4
	v_mov_b32_e32 v107, v4
	v_mov_b32_e32 v108, v4
	v_mov_b32_e32 v109, v4
	v_mov_b32_e32 v110, v4
	v_mov_b32_e32 v111, v4
	v_mov_b32_e32 v120, v4
	v_mov_b32_e32 v121, v4
	v_mov_b32_e32 v122, v4
	v_mov_b32_e32 v123, v4
	v_mov_b32_e32 v124, v4
	v_mov_b32_e32 v125, v4
	v_mov_b32_e32 v126, v4
	v_mov_b32_e32 v127, v4
	v_mov_b32_e32 v136, v4
	v_mov_b32_e32 v137, v4
	v_mov_b32_e32 v138, v4
	v_mov_b32_e32 v139, v4
	v_mov_b32_e32 v140, v4
	v_mov_b32_e32 v141, v4
	v_mov_b32_e32 v142, v4
	v_mov_b32_e32 v143, v4
	.p2align 6
	s_nop 0
	s_nop 0
	s_nop 0
	s_nop 0
	s_nop 0
	s_nop 0
	s_nop 0
	s_nop 0
	s_nop 0
	s_nop 0
	s_nop 0
	s_nop 0
	s_nop 0
	s_nop 0
	s_nop 0

; template <class Epi, class Sched, bool ALIGN_EPI = false, bool SP2 = false>
; __device__ __forceinline__ void gemm_phase(LAS unsigned char* lds, const Gemm g, const Sched& S, const Epi& E, const int tid) {
;     ...
;     for (;;) {
;         const bool has_next = S.next(ui + 1, nxt);
;         const char* nA = has_next ? (const char*)g.A + (size_t)nxt.pm * tstep : cA; const char* nB = has_next ? (const char*)g.Bt + (size_t)nxt.pn * tstep : cB;
;         for (int t = 0; t < nt; t += 2) {
;             const bool last = (t == nt - 2);
;             const char* a1 = cA + (size_t)(t + 1) * kstep;
;             const char* a2 = last ? nA : cA + (size_t)(t + 2) * kstep; const char* b2 = last ? nB : cB + (size_t)(t + 2) * kstep;
;     ...
; #pragma unroll
;         for (int a = 0; a < 2; ++a)
; #pragma unroll
;             for (int b = 0; b < 2; ++b)
; #pragma unroll
;                 for (int m = 0; m < 4; ++m)
; #pragma unroll
;                     for (int n = 0; n < 2; ++n) acc[a][b][m][n] = (f32x4){0.f, 0.f, 0.f, 0.f};
;         cur = nxt; cA = nA; cB = nB; ++ui;
.LBB0_1354:
	s_ashr_i32 s15, s14, 31
	s_lshl_b64 s[16:17], s[14:15], 20
	s_add_u32 s16, s34, s16
	s_addc_u32 s17, s35, s17
	s_and_b64 s[18:19], s[4:5], exec
	s_cselect_b32 s1, s17, s23
	s_cselect_b32 s15, s16, s22
	s_ashr_i32 s13, s12, 31
	s_lshl_b64 s[18:19], s[12:13], 20
	s_add_u32 s18, s36, s18
	s_addc_u32 s19, s37, s19
	s_and_b64 s[26:27], s[4:5], exec
	s_cselect_b32 s13, s19, s25
	s_cselect_b32 s21, s18, s24
	s_add_u32 s51, s24, 0x100
	v_mov_b32_e32 v0, 0
	s_addc_u32 s52, s25, 0
	s_mov_b32 s53, -2
	s_waitcnt lgkmcnt(0)
	v_mov_b32_e32 v1, v0
	v_mov_b32_e32 v2, v0
	v_mov_b32_e32 v3, v0
	v_mov_b32_e32 v4, v0
	v_mov_b32_e32 v5, v0
	v_mov_b32_e32 v6, v0
	v_mov_b32_e32 v7, v0
	v_mov_b32_e32 v16, v0
	v_mov_b32_e32 v17, v0
	v_mov_b32_e32 v18, v0
	v_mov_b32_e32 v19, v0
	v_mov_b32_e32 v20, v0
	v_mov_b32_e32 v21, v0
	v_mov_b32_e32 v22, v0
	v_mov_b32_e32 v23, v0
	v_mov_b32_e32 v32, v0
	v_mov_b32_e32 v33, v0
	v_mov_b32_e32 v34, v0
	v_mov_b32_e32 v35, v0
	v_mov_b32_e32 v36, v0
	v_mov_b32_e32 v37, v0
	v_mov_b32_e32 v38, v0
	v_mov_b32_e32 v39, v0
	v_mov_b32_e32 v48, v0
	v_mov_b32_e32 v49, v0
	s_waitcnt vmcnt(0)
	v_mov_b32_e32 v50, v0
	v_mov_b32_e32 v51, v0
	v_mov_b32_e32 v52, v0
	v_mov_b32_e32 v53, v0
	v_mov_b32_e32 v54, v0
	v_mov_b32_e32 v55, v0
	v_mov_b32_e32 v8, v0
	v_mov_b32_e32 v9, v0
	v_mov_b32_e32 v10, v0
	v_mov_b32_e32 v11, v0
	v_mov_b32_e32 v12, v0
	v_mov_b32_e32 v13, v0
	v_mov_b32_e32 v14, v0
	v_mov_b32_e32 v15, v0
	v_mov_b32_e32 v24, v0
	v_mov_b32_e32 v25, v0
	v_mov_b32_e32 v26, v0
	v_mov_b32_e32 v27, v0
	v_mov_b32_e32 v28, v0
	v_mov_b32_e32 v29, v0
	v_mov_b32_e32 v30, v0
	v_mov_b32_e32 v31, v0
	v_mov_b32_e32 v40, v0
	v_mov_b32_e32 v41, v0
	v_mov_b32_e32 v42, v0
	v_mov_b32_e32 v43, v0
	v_mov_b32_e32 v44, v0
	v_mov_b32_e32 v45, v0
	v_mov_b32_e32 v46, v0
	v_mov_b32_e32 v47, v0
	v_mov_b32_e32 v56, v0
	v_mov_b32_e32 v57, v0
	v_mov_b32_e32 v58, v0
	v_mov_b32_e32 v59, v0
	v_mov_b32_e32 v60, v0
	v_mov_b32_e32 v61, v0
	v_mov_b32_e32 v62, v0
	v_mov_b32_e32 v63, v0
	v_mov_b32_e32 v64, v0
	v_mov_b32_e32 v65, v0
	v_mov_b32_e32 v66, v0
	v_mov_b32_e32 v67, v0
	v_mov_b32_e32 v68, v0
	v_mov_b32_e32 v69, v0
	v_mov_b32_e32 v70, v0
	v_mov_b32_e32 v71, v0
	v_mov_b32_e32 v80, v0
	v_mov_b32_e32 v81, v0
	v_mov_b32_e32 v82, v0
	v_mov_b32_e32 v83, v0
	v_mov_b32_e32 v84, v0
	v_mov_b32_e32 v85, v0
	v_mov_b32_e32 v86, v0
	v_mov_b32_e32 v87, v0
	v_mov_b32_e32 v96, v0
	v_mov_b32_e32 v97, v0
	v_mov_b32_e32 v98, v0
	v_mov_b32_e32 v99, v0
	v_mov_b32_e32 v100, v0
	v_mov_b32_e32 v101, v0
	v_mov_b32_e32 v102, v0
	v_mov_b32_e32 v103, v0
	v_mov_b32_e32 v112, v0
	v_mov_b32_e32 v113, v0
	v_mov_b32_e32 v114, v0
	v_mov_b32_e32 v115, v0
	v_mov_b32_e32 v116, v0
	v_mov_b32_e32 v117, v0
	v_mov_b32_e32 v118, v0
	v_mov_b32_e32 v119, v0
	v_mov_b32_e32 v72, v0
	v_mov_b32_e32 v73, v0
	v_mov_b32_e32 v74, v0
	v_mov_b32_e32 v75, v0
	v_mov_b32_e32 v76, v0
	v_mov_b32_e32 v77, v0
	v_mov_b32_e32 v78, v0
	v_mov_b32_e32 v79, v0
	v_mov_b32_e32 v88, v0
	v_mov_b32_e32 v89, v0
	v_mov_b32_e32 v90, v0
	v_mov_b32_e32 v91, v0
	v_mov_b32_e32 v92, v0
	v_mov_b32_e32 v93, v0
	v_mov_b32_e32 v94, v0
	v_mov_b32_e32 v95, v0
	v_mov_b32_e32 v104, v0
	v_mov_b32_e32 v105, v0
	v_mov_b32_e32 v106, v0
	v_mov_b32_e32 v107, v0
	v_mov_b32_e32 v108, v0
	v_mov_b32_e32 v109, v0
	v_mov_b32_e32 v110, v0
	v_mov_b32_e32 v111, v0
	v_mov_b32_e32 v120, v0
	v_mov_b32_e32 v121, v0
	v_mov_b32_e32 v122, v0
	v_mov_b32_e32 v123, v0
	v_mov_b32_e32 v124, v0
	v_mov_b32_e32 v125, v0
	v_mov_b32_e32 v126, v0
	v_mov_b32_e32 v127, v0
	.p2align 6
	s_nop 0
	s_nop 0
	s_nop 0
	s_nop 0
	s_nop 0
	s_nop 0
	s_nop 0
	s_nop 0
	s_nop 0
	s_nop 0
	s_nop 0
	s_nop 0

; template <class Epi, class Sched, bool ALIGN_EPI = false, bool SP2 = false>
; __device__ __forceinline__ void gemm_phase(LAS unsigned char* lds, const Gemm g, const Sched& S, const Epi& E, const int tid) {
;     ...
;     for (;;) {
;         const bool has_next = S.next(ui + 1, nxt);
;         const char* nA = has_next ? (const char*)g.A + (size_t)nxt.pm * tstep : cA; const char* nB = has_next ? (const char*)g.Bt + (size_t)nxt.pn * tstep : cB;
;         for (int t = 0; t < nt; t += 2) {
;             const bool last = (t == nt - 2);
;             const char* a1 = cA + (size_t)(t + 1) * kstep;
;             const char* a2 = last ? nA : cA + (size_t)(t + 2) * kstep; const char* b2 = last ? nB : cB + (size_t)(t + 2) * kstep;
;     ...
; #pragma unroll
;         for (int a = 0; a < 2; ++a)
; #pragma unroll
;             for (int b = 0; b < 2; ++b)
; #pragma unroll
;                 for (int m = 0; m < 4; ++m)
; #pragma unroll
;                     for (int n = 0; n < 2; ++n) acc[a][b][m][n] = (f32x4){0.f, 0.f, 0.f, 0.f};
;         cur = nxt; cA = nA; cB = nB; ++ui;
.LBB0_1486:
	s_add_u32 s47, s16, 0x100
	v_mov_b32_e32 v0, 0
	s_addc_u32 s48, s17, 0
	s_mov_b32 s49, -2
	s_waitcnt lgkmcnt(0)
	v_mov_b32_e32 v1, v0
	v_mov_b32_e32 v2, v0
	v_mov_b32_e32 v3, v0
	v_mov_b32_e32 v4, v0
	v_mov_b32_e32 v5, v0
	v_mov_b32_e32 v6, v0
	v_mov_b32_e32 v7, v0
	v_mov_b32_e32 v16, v0
	v_mov_b32_e32 v17, v0
	v_mov_b32_e32 v18, v0
	v_mov_b32_e32 v19, v0
	v_mov_b32_e32 v20, v0
	v_mov_b32_e32 v21, v0
	v_mov_b32_e32 v22, v0
	v_mov_b32_e32 v23, v0
	v_mov_b32_e32 v32, v0
	v_mov_b32_e32 v33, v0
	v_mov_b32_e32 v34, v0
	v_mov_b32_e32 v35, v0
	v_mov_b32_e32 v36, v0
	v_mov_b32_e32 v37, v0
	v_mov_b32_e32 v38, v0
	v_mov_b32_e32 v39, v0
	v_mov_b32_e32 v48, v0
	v_mov_b32_e32 v49, v0
	v_mov_b32_e32 v50, v0
	v_mov_b32_e32 v51, v0
	v_mov_b32_e32 v52, v0
	v_mov_b32_e32 v53, v0
	v_mov_b32_e32 v54, v0
	v_mov_b32_e32 v55, v0
	v_mov_b32_e32 v8, v0
	v_mov_b32_e32 v9, v0
	v_mov_b32_e32 v10, v0
	v_mov_b32_e32 v11, v0
	v_mov_b32_e32 v12, v0
	v_mov_b32_e32 v13, v0
	v_mov_b32_e32 v14, v0
	v_mov_b32_e32 v15, v0
	v_mov_b32_e32 v24, v0
	v_mov_b32_e32 v25, v0
	v_mov_b32_e32 v26, v0
	v_mov_b32_e32 v27, v0
	v_mov_b32_e32 v28, v0
	v_mov_b32_e32 v29, v0
	v_mov_b32_e32 v30, v0
	v_mov_b32_e32 v31, v0
	v_mov_b32_e32 v40, v0
	v_mov_b32_e32 v41, v0
	v_mov_b32_e32 v42, v0
	v_mov_b32_e32 v43, v0
	v_mov_b32_e32 v44, v0
	v_mov_b32_e32 v45, v0
	v_mov_b32_e32 v46, v0
	v_mov_b32_e32 v47, v0
	v_mov_b32_e32 v56, v0
	v_mov_b32_e32 v57, v0
	v_mov_b32_e32 v58, v0
	v_mov_b32_e32 v59, v0
	v_mov_b32_e32 v60, v0
	v_mov_b32_e32 v61, v0
	v_mov_b32_e32 v62, v0
	v_mov_b32_e32 v63, v0
	v_mov_b32_e32 v64, v0
	v_mov_b32_e32 v65, v0
	v_mov_b32_e32 v66, v0
	v_mov_b32_e32 v67, v0
	v_mov_b32_e32 v68, v0
	v_mov_b32_e32 v69, v0
	v_mov_b32_e32 v70, v0
	v_mov_b32_e32 v71, v0
	v_mov_b32_e32 v80, v0
	v_mov_b32_e32 v81, v0
	v_mov_b32_e32 v82, v0
	v_mov_b32_e32 v83, v0
	v_mov_b32_e32 v84, v0
	v_mov_b32_e32 v85, v0
	v_mov_b32_e32 v86, v0
	v_mov_b32_e32 v87, v0
	v_mov_b32_e32 v96, v0
	v_mov_b32_e32 v97, v0
	v_mov_b32_e32 v98, v0
	v_mov_b32_e32 v99, v0
	v_mov_b32_e32 v100, v0
	v_mov_b32_e32 v101, v0
	v_mov_b32_e32 v102, v0
	v_mov_b32_e32 v103, v0
	v_mov_b32_e32 v112, v0
	v_mov_b32_e32 v113, v0
	v_mov_b32_e32 v114, v0
	v_mov_b32_e32 v115, v0
	v_mov_b32_e32 v116, v0
	v_mov_b32_e32 v117, v0
	v_mov_b32_e32 v118, v0
	v_mov_b32_e32 v119, v0
	v_mov_b32_e32 v72, v0
	v_mov_b32_e32 v73, v0
	v_mov_b32_e32 v74, v0
	v_mov_b32_e32 v75, v0
	v_mov_b32_e32 v76, v0
	v_mov_b32_e32 v77, v0
	v_mov_b32_e32 v78, v0
	v_mov_b32_e32 v79, v0
	v_mov_b32_e32 v88, v0
	v_mov_b32_e32 v89, v0
	v_mov_b32_e32 v90, v0
	v_mov_b32_e32 v91, v0
	v_mov_b32_e32 v92, v0
	v_mov_b32_e32 v93, v0
	v_mov_b32_e32 v94, v0
	v_mov_b32_e32 v95, v0
	v_mov_b32_e32 v104, v0
	v_mov_b32_e32 v105, v0
	v_mov_b32_e32 v106, v0
	v_mov_b32_e32 v107, v0
	v_mov_b32_e32 v108, v0
	v_mov_b32_e32 v109, v0
	v_mov_b32_e32 v110, v0
	v_mov_b32_e32 v111, v0
	v_mov_b32_e32 v120, v0
	v_mov_b32_e32 v121, v0
	v_mov_b32_e32 v122, v0
	v_mov_b32_e32 v123, v0
	v_mov_b32_e32 v124, v0
	v_mov_b32_e32 v125, v0
	v_mov_b32_e32 v126, v0
	v_mov_b32_e32 v127, v0
	.p2align 6
	s_nop 0
	s_nop 0
	s_nop 0
	s_nop 0
	s_nop 0
